# P0 modulation unit: batched the 16 c loads of the silu staging loop (counted vmcnt); stacked on attention edits + GEMM no-setprio
# speedup vs baseline: 1.0088x; 1.0088x over previous
; __device__ __forceinline__ void p0_mod_unit(const float* __restrict__ c, const float* __restrict__ w_ada, const float* __restrict__ b_ada, float* __restrict__ mod, int unit, LAS float* lds, int tid) {
;     ...
;     const int l = unit / 96, j0 = (unit % 96) * 64, col = tid & 63, kq = tid >> 6;
;     for (int i = tid; i < 8192; i += NTHR) { const float v = c[i]; sc[i] = v / (1.f + __expf(-v)); }
;     __syncthreads();
.LBB0_36:
	global_load_dword v14, v[2:3], off
	v_lshl_add_u64 v[2:3], v[2:3], 0, s[10:11]
	global_load_dword v15, v[2:3], off
	v_lshl_add_u64 v[2:3], v[2:3], 0, s[10:11]
	global_load_dword v16, v[2:3], off
	v_lshl_add_u64 v[2:3], v[2:3], 0, s[10:11]
	global_load_dword v17, v[2:3], off
	v_lshl_add_u64 v[2:3], v[2:3], 0, s[10:11]
	global_load_dword v18, v[2:3], off
	v_lshl_add_u64 v[2:3], v[2:3], 0, s[10:11]
	global_load_dword v19, v[2:3], off
	v_lshl_add_u64 v[2:3], v[2:3], 0, s[10:11]
	global_load_dword v20, v[2:3], off
	v_lshl_add_u64 v[2:3], v[2:3], 0, s[10:11]
	global_load_dword v21, v[2:3], off
	v_lshl_add_u64 v[2:3], v[2:3], 0, s[10:11]
	global_load_dword v22, v[2:3], off
	v_lshl_add_u64 v[2:3], v[2:3], 0, s[10:11]
	global_load_dword v23, v[2:3], off
	v_lshl_add_u64 v[2:3], v[2:3], 0, s[10:11]
	global_load_dword v24, v[2:3], off
	v_lshl_add_u64 v[2:3], v[2:3], 0, s[10:11]
	global_load_dword v25, v[2:3], off
	v_lshl_add_u64 v[2:3], v[2:3], 0, s[10:11]
	global_load_dword v26, v[2:3], off
	v_lshl_add_u64 v[2:3], v[2:3], 0, s[10:11]
	global_load_dword v27, v[2:3], off
	v_lshl_add_u64 v[2:3], v[2:3], 0, s[10:11]
	global_load_dword v28, v[2:3], off
	v_lshl_add_u64 v[2:3], v[2:3], 0, s[10:11]
	global_load_dword v29, v[2:3], off
	s_waitcnt vmcnt(15)
	v_mul_f32_e32 v7, 0xbfb8aa3b, v14
	v_exp_f32_e32 v7, v7
	s_nop 0
	v_add_f32_e32 v7, 1.0, v7
	v_div_scale_f32 v8, s[20:21], v7, v7, v14
	v_rcp_f32_e32 v9, v8
	v_div_scale_f32 v10, vcc, v14, v7, v14
	v_fma_f32 v11, -v8, v9, 1.0
	v_fmac_f32_e32 v9, v11, v9
	v_mul_f32_e32 v11, v10, v9
	v_fma_f32 v12, -v8, v11, v10
	v_fmac_f32_e32 v11, v12, v9
	v_fma_f32 v8, -v8, v11, v10
	v_div_fmas_f32 v8, v8, v9, v11
	v_div_fixup_f32 v6, v8, v7, v14
	ds_write_b32 v4, v6
	v_add_u32_e32 v4, 0x800, v4
	s_waitcnt vmcnt(14)
	v_mul_f32_e32 v7, 0xbfb8aa3b, v15
	v_exp_f32_e32 v7, v7
	s_nop 0
	v_add_f32_e32 v7, 1.0, v7
	v_div_scale_f32 v8, s[20:21], v7, v7, v15
	v_rcp_f32_e32 v9, v8
	v_div_scale_f32 v10, vcc, v15, v7, v15
	v_fma_f32 v11, -v8, v9, 1.0
	v_fmac_f32_e32 v9, v11, v9
	v_mul_f32_e32 v11, v10, v9
	v_fma_f32 v12, -v8, v11, v10
	v_fmac_f32_e32 v11, v12, v9
	v_fma_f32 v8, -v8, v11, v10
	v_div_fmas_f32 v8, v8, v9, v11
	v_div_fixup_f32 v6, v8, v7, v15
	ds_write_b32 v4, v6
	v_add_u32_e32 v4, 0x800, v4
	s_waitcnt vmcnt(13)
	v_mul_f32_e32 v7, 0xbfb8aa3b, v16
	v_exp_f32_e32 v7, v7
	s_nop 0
	v_add_f32_e32 v7, 1.0, v7
	v_div_scale_f32 v8, s[20:21], v7, v7, v16
	v_rcp_f32_e32 v9, v8
	v_div_scale_f32 v10, vcc, v16, v7, v16
	v_fma_f32 v11, -v8, v9, 1.0
	v_fmac_f32_e32 v9, v11, v9
	v_mul_f32_e32 v11, v10, v9
	v_fma_f32 v12, -v8, v11, v10
	v_fmac_f32_e32 v11, v12, v9
	v_fma_f32 v8, -v8, v11, v10
	v_div_fmas_f32 v8, v8, v9, v11
	v_div_fixup_f32 v6, v8, v7, v16
	ds_write_b32 v4, v6
	v_add_u32_e32 v4, 0x800, v4
	s_waitcnt vmcnt(12)
	v_mul_f32_e32 v7, 0xbfb8aa3b, v17
	v_exp_f32_e32 v7, v7
	s_nop 0
	v_add_f32_e32 v7, 1.0, v7
	v_div_scale_f32 v8, s[20:21], v7, v7, v17
	v_rcp_f32_e32 v9, v8
	v_div_scale_f32 v10, vcc, v17, v7, v17
	v_fma_f32 v11, -v8, v9, 1.0
	v_fmac_f32_e32 v9, v11, v9
	v_mul_f32_e32 v11, v10, v9
	v_fma_f32 v12, -v8, v11, v10
	v_fmac_f32_e32 v11, v12, v9
	v_fma_f32 v8, -v8, v11, v10
	v_div_fmas_f32 v8, v8, v9, v11
	v_div_fixup_f32 v6, v8, v7, v17
	ds_write_b32 v4, v6
	v_add_u32_e32 v4, 0x800, v4
	s_waitcnt vmcnt(11)
	v_mul_f32_e32 v7, 0xbfb8aa3b, v18
	v_exp_f32_e32 v7, v7
	s_nop 0
	v_add_f32_e32 v7, 1.0, v7
	v_div_scale_f32 v8, s[20:21], v7, v7, v18
	v_rcp_f32_e32 v9, v8
	v_div_scale_f32 v10, vcc, v18, v7, v18
	v_fma_f32 v11, -v8, v9, 1.0
	v_fmac_f32_e32 v9, v11, v9
	v_mul_f32_e32 v11, v10, v9
	v_fma_f32 v12, -v8, v11, v10
	v_fmac_f32_e32 v11, v12, v9
	v_fma_f32 v8, -v8, v11, v10
	v_div_fmas_f32 v8, v8, v9, v11
	v_div_fixup_f32 v6, v8, v7, v18
	ds_write_b32 v4, v6
	v_add_u32_e32 v4, 0x800, v4
	s_waitcnt vmcnt(10)
	v_mul_f32_e32 v7, 0xbfb8aa3b, v19
	v_exp_f32_e32 v7, v7
	s_nop 0
	v_add_f32_e32 v7, 1.0, v7
	v_div_scale_f32 v8, s[20:21], v7, v7, v19
	v_rcp_f32_e32 v9, v8
	v_div_scale_f32 v10, vcc, v19, v7, v19
	v_fma_f32 v11, -v8, v9, 1.0
	v_fmac_f32_e32 v9, v11, v9
	v_mul_f32_e32 v11, v10, v9
	v_fma_f32 v12, -v8, v11, v10
	v_fmac_f32_e32 v11, v12, v9
	v_fma_f32 v8, -v8, v11, v10
	v_div_fmas_f32 v8, v8, v9, v11
	v_div_fixup_f32 v6, v8, v7, v19
	ds_write_b32 v4, v6
	v_add_u32_e32 v4, 0x800, v4
	s_waitcnt vmcnt(9)
	v_mul_f32_e32 v7, 0xbfb8aa3b, v20
	v_exp_f32_e32 v7, v7
	s_nop 0
	v_add_f32_e32 v7, 1.0, v7
	v_div_scale_f32 v8, s[20:21], v7, v7, v20
	v_rcp_f32_e32 v9, v8
	v_div_scale_f32 v10, vcc, v20, v7, v20
	v_fma_f32 v11, -v8, v9, 1.0
	v_fmac_f32_e32 v9, v11, v9
	v_mul_f32_e32 v11, v10, v9
	v_fma_f32 v12, -v8, v11, v10
	v_fmac_f32_e32 v11, v12, v9
	v_fma_f32 v8, -v8, v11, v10
	v_div_fmas_f32 v8, v8, v9, v11
	v_div_fixup_f32 v6, v8, v7, v20
	ds_write_b32 v4, v6
	v_add_u32_e32 v4, 0x800, v4
	s_waitcnt vmcnt(8)
	v_mul_f32_e32 v7, 0xbfb8aa3b, v21
	v_exp_f32_e32 v7, v7
	s_nop 0
	v_add_f32_e32 v7, 1.0, v7
	v_div_scale_f32 v8, s[20:21], v7, v7, v21
	v_rcp_f32_e32 v9, v8
	v_div_scale_f32 v10, vcc, v21, v7, v21
	v_fma_f32 v11, -v8, v9, 1.0
	v_fmac_f32_e32 v9, v11, v9
	v_mul_f32_e32 v11, v10, v9
	v_fma_f32 v12, -v8, v11, v10
	v_fmac_f32_e32 v11, v12, v9
	v_fma_f32 v8, -v8, v11, v10
	v_div_fmas_f32 v8, v8, v9, v11
	v_div_fixup_f32 v6, v8, v7, v21
	ds_write_b32 v4, v6
	v_add_u32_e32 v4, 0x800, v4
	s_waitcnt vmcnt(7)
; __device__ __forceinline__ void p0_mod_unit(const float* __restrict__ c, const float* __restrict__ w_ada, const float* __restrict__ b_ada, float* __restrict__ mod, int unit, LAS float* lds, int tid) {
;     ...
;     const int l = unit / 96, j0 = (unit % 96) * 64, col = tid & 63, kq = tid >> 6;
;     for (int i = tid; i < 8192; i += NTHR) { const float v = c[i]; sc[i] = v / (1.f + __expf(-v)); }
;     __syncthreads();
;     float acc[8] = {0.f, 0.f, 0.f, 0.f, 0.f, 0.f, 0.f, 0.f};
;     const float* w = w_ada + (size_t)l * 1024 * 6144 + j0 + col;
;     for (int k = kq * 128; k < kq * 128 + 128; k += 16) { float wv[16];
	v_mul_f32_e32 v7, 0xbfb8aa3b, v22
	v_exp_f32_e32 v7, v7
	s_nop 0
	v_add_f32_e32 v7, 1.0, v7
	v_div_scale_f32 v8, s[20:21], v7, v7, v22
	v_rcp_f32_e32 v9, v8
	v_div_scale_f32 v10, vcc, v22, v7, v22
	v_fma_f32 v11, -v8, v9, 1.0
	v_fmac_f32_e32 v9, v11, v9
	v_mul_f32_e32 v11, v10, v9
	v_fma_f32 v12, -v8, v11, v10
	v_fmac_f32_e32 v11, v12, v9
	v_fma_f32 v8, -v8, v11, v10
	v_div_fmas_f32 v8, v8, v9, v11
	v_div_fixup_f32 v6, v8, v7, v22
	ds_write_b32 v4, v6
	v_add_u32_e32 v4, 0x800, v4
	s_waitcnt vmcnt(6)
	v_mul_f32_e32 v7, 0xbfb8aa3b, v23
	v_exp_f32_e32 v7, v7
	s_nop 0
	v_add_f32_e32 v7, 1.0, v7
	v_div_scale_f32 v8, s[20:21], v7, v7, v23
	v_rcp_f32_e32 v9, v8
	v_div_scale_f32 v10, vcc, v23, v7, v23
	v_fma_f32 v11, -v8, v9, 1.0
	v_fmac_f32_e32 v9, v11, v9
	v_mul_f32_e32 v11, v10, v9
	v_fma_f32 v12, -v8, v11, v10
	v_fmac_f32_e32 v11, v12, v9
	v_fma_f32 v8, -v8, v11, v10
	v_div_fmas_f32 v8, v8, v9, v11
	v_div_fixup_f32 v6, v8, v7, v23
	ds_write_b32 v4, v6
	v_add_u32_e32 v4, 0x800, v4
	s_waitcnt vmcnt(5)
	v_mul_f32_e32 v7, 0xbfb8aa3b, v24
	v_exp_f32_e32 v7, v7
	s_nop 0
	v_add_f32_e32 v7, 1.0, v7
	v_div_scale_f32 v8, s[20:21], v7, v7, v24
	v_rcp_f32_e32 v9, v8
	v_div_scale_f32 v10, vcc, v24, v7, v24
	v_fma_f32 v11, -v8, v9, 1.0
	v_fmac_f32_e32 v9, v11, v9
	v_mul_f32_e32 v11, v10, v9
	v_fma_f32 v12, -v8, v11, v10
	v_fmac_f32_e32 v11, v12, v9
	v_fma_f32 v8, -v8, v11, v10
	v_div_fmas_f32 v8, v8, v9, v11
	v_div_fixup_f32 v6, v8, v7, v24
	ds_write_b32 v4, v6
	v_add_u32_e32 v4, 0x800, v4
	s_waitcnt vmcnt(4)
	v_mul_f32_e32 v7, 0xbfb8aa3b, v25
	v_exp_f32_e32 v7, v7
	s_nop 0
	v_add_f32_e32 v7, 1.0, v7
	v_div_scale_f32 v8, s[20:21], v7, v7, v25
	v_rcp_f32_e32 v9, v8
	v_div_scale_f32 v10, vcc, v25, v7, v25
	v_fma_f32 v11, -v8, v9, 1.0
	v_fmac_f32_e32 v9, v11, v9
	v_mul_f32_e32 v11, v10, v9
	v_fma_f32 v12, -v8, v11, v10
	v_fmac_f32_e32 v11, v12, v9
	v_fma_f32 v8, -v8, v11, v10
	v_div_fmas_f32 v8, v8, v9, v11
	v_div_fixup_f32 v6, v8, v7, v25
	ds_write_b32 v4, v6
	v_add_u32_e32 v4, 0x800, v4
	s_waitcnt vmcnt(3)
	v_mul_f32_e32 v7, 0xbfb8aa3b, v26
	v_exp_f32_e32 v7, v7
	s_nop 0
	v_add_f32_e32 v7, 1.0, v7
	v_div_scale_f32 v8, s[20:21], v7, v7, v26
	v_rcp_f32_e32 v9, v8
	v_div_scale_f32 v10, vcc, v26, v7, v26
	v_fma_f32 v11, -v8, v9, 1.0
	v_fmac_f32_e32 v9, v11, v9
	v_mul_f32_e32 v11, v10, v9
	v_fma_f32 v12, -v8, v11, v10
	v_fmac_f32_e32 v11, v12, v9
	v_fma_f32 v8, -v8, v11, v10
	v_div_fmas_f32 v8, v8, v9, v11
	v_div_fixup_f32 v6, v8, v7, v26
	ds_write_b32 v4, v6
	v_add_u32_e32 v4, 0x800, v4
	s_waitcnt vmcnt(2)
	v_mul_f32_e32 v7, 0xbfb8aa3b, v27
	v_exp_f32_e32 v7, v7
	s_nop 0
	v_add_f32_e32 v7, 1.0, v7
	v_div_scale_f32 v8, s[20:21], v7, v7, v27
	v_rcp_f32_e32 v9, v8
	v_div_scale_f32 v10, vcc, v27, v7, v27
	v_fma_f32 v11, -v8, v9, 1.0
	v_fmac_f32_e32 v9, v11, v9
	v_mul_f32_e32 v11, v10, v9
	v_fma_f32 v12, -v8, v11, v10
	v_fmac_f32_e32 v11, v12, v9
	v_fma_f32 v8, -v8, v11, v10
	v_div_fmas_f32 v8, v8, v9, v11
	v_div_fixup_f32 v6, v8, v7, v27
	ds_write_b32 v4, v6
	v_add_u32_e32 v4, 0x800, v4
	s_waitcnt vmcnt(1)
	v_mul_f32_e32 v7, 0xbfb8aa3b, v28
	v_exp_f32_e32 v7, v7
	s_nop 0
	v_add_f32_e32 v7, 1.0, v7
	v_div_scale_f32 v8, s[20:21], v7, v7, v28
	v_rcp_f32_e32 v9, v8
	v_div_scale_f32 v10, vcc, v28, v7, v28
	v_fma_f32 v11, -v8, v9, 1.0
	v_fmac_f32_e32 v9, v11, v9
	v_mul_f32_e32 v11, v10, v9
	v_fma_f32 v12, -v8, v11, v10
	v_fmac_f32_e32 v11, v12, v9
	v_fma_f32 v8, -v8, v11, v10
	v_div_fmas_f32 v8, v8, v9, v11
	v_div_fixup_f32 v6, v8, v7, v28
	ds_write_b32 v4, v6
	v_add_u32_e32 v4, 0x800, v4
	s_waitcnt vmcnt(0)
	v_mul_f32_e32 v7, 0xbfb8aa3b, v29
	v_exp_f32_e32 v7, v7
	s_nop 0
	v_add_f32_e32 v7, 1.0, v7
	v_div_scale_f32 v8, s[20:21], v7, v7, v29
	v_rcp_f32_e32 v9, v8
	v_div_scale_f32 v10, vcc, v29, v7, v29
	v_fma_f32 v11, -v8, v9, 1.0
	v_fmac_f32_e32 v9, v11, v9
	v_mul_f32_e32 v11, v10, v9
	v_fma_f32 v12, -v8, v11, v10
	v_fmac_f32_e32 v11, v12, v9
	v_fma_f32 v8, -v8, v11, v10
	v_div_fmas_f32 v8, v8, v9, v11
	v_div_fixup_f32 v6, v8, v7, v29
	ds_write_b32 v4, v6
	v_add_u32_e32 v4, 0x800, v4
	s_or_b64 exec, exec, s[18:19]
	s_mul_hi_i32 s18, s29, 0x2aaaaaab
	s_lshr_b32 s19, s18, 31
	s_ashr_i32 s18, s18, 4
	s_add_i32 s20, s18, s19
	s_mul_i32 s18, s20, 0x60
	s_sub_i32 s18, s29, s18
	s_lshl_b32 s18, s18, 6
	s_ashr_i32 s19, s18, 31
	s_ashr_i32 s21, s20, 31
	s_mul_i32 s23, s20, 0x1800000
	v_lshl_add_u64 v[2:3], s[4:5], 0, v[138:139]
	s_lshl_b64 s[4:5], s[18:19], 2
	s_mul_hi_i32 s22, s20, 0x1800000
	s_add_u32 s4, s23, s4
	s_addc_u32 s5, s22, s5
	v_mov_b32_e32 v142, 0
	v_lshl_add_u64 v[140:141], v[2:3], 0, s[4:5]
	s_mov_b64 s[22:23], 0
	v_mov_b32_e32 v134, v156
	v_mov_b32_e32 v157, v1
	v_mov_b32_e32 v143, v142
	v_mov_b32_e32 v144, v142
	v_mov_b32_e32 v145, v142
	v_mov_b32_e32 v146, v142
	v_mov_b32_e32 v147, v142
	v_mov_b32_e32 v148, v142
	v_mov_b32_e32 v149, v142
	s_waitcnt lgkmcnt(0)
	s_barrier
